# weight-conversion tile loop software-pipelined: next tile's row loads issued into a second register set during the current tile's convert/store
# baseline (speedup 1.0000x reference)
.LBB0_35:
	s_waitcnt vmcnt(2)
.Lconv_b1:
	v_add_u32_e32 v2, 0x2040, v43
	ds_write2_b32 v43, v76, v77 offset1:1
	ds_write2_b32 v43, v78, v79 offset0:2 offset1:3
	ds_write2_b32 v2, v80, v81 offset1:1
	v_add_u32_e32 v2, 0x2048, v43
	ds_write2_b32 v2, v82, v83 offset1:1
	v_add_u32_e32 v2, 0x4080, v43
	ds_write2_b32 v2, v84, v85 offset1:1
	v_add_u32_e32 v2, 0x4088, v43
	ds_write2_b32 v2, v86, v87 offset1:1
	v_add_u32_e32 v2, 0x60c0, v43
	ds_write2_b32 v2, v88, v89 offset1:1
	v_add_u32_e32 v2, 0x60c8, v43
	v_add_u32_e32 v4, 0x400, v44
	v_add_u32_e32 v6, 0x800, v44
	v_add_u32_e32 v8, 0xc00, v44
	v_add_u32_e32 v15, 0x1800, v44
	ds_write2_b32 v2, v90, v91 offset1:1
	s_waitcnt lgkmcnt(0)
	s_barrier
	ds_read2_b32 v[2:3], v44 offset1:129
	ds_read2_b32 v[4:5], v4 offset0:2 offset1:131
	ds_read2_b32 v[6:7], v6 offset0:4 offset1:133
	ds_read2_b32 v[8:9], v8 offset0:6 offset1:135
	v_add_u32_e32 v10, 0x1000, v44
	v_add_u32_e32 v12, 0x1400, v44
	ds_read2_b32 v[16:17], v15 offset0:12 offset1:141
	v_add_u32_e32 v15, 0x1c00, v44
	ds_read2_b32 v[10:11], v10 offset0:8 offset1:137
	ds_read2_b32 v[12:13], v12 offset0:10 offset1:139
	ds_read2_b32 v[18:19], v15 offset0:14 offset1:143
	v_add_u32_e32 v15, s34, v42
	v_mad_i64_i32 v[20:21], s[0:1], v15, s6, 0
	v_lshl_add_u64 v[20:21], v[20:21], 1, s[10:11]
	s_ashr_i32 s21, s20, 31
	v_lshl_add_u64 v[20:21], s[20:21], 1, v[20:21]
	v_mov_b32_e32 v35, v14
	v_lshl_add_u64 v[20:21], v[20:21], 0, v[34:35]
	s_add_i32 s33, s33, s18
	s_add_i32 s29, s29, s22
	s_cmp_ge_i32 s33, s7
	s_cbranch_scc1 .Lconv_nopf
	s_abs_i32 s1, s33
	s_mul_hi_u32 s20, s1, s31
	s_mul_i32 s21, s20, s26
	s_ashr_i32 s0, s33, 31
	s_sub_i32 s1, s1, s21
	s_xor_b32 s0, s0, s28
	s_add_i32 s21, s20, 1
	s_sub_i32 s34, s1, s26
	s_cmp_ge_u32 s1, s26
	s_cselect_b32 s20, s21, s20
	s_cselect_b32 s1, s34, s1
	s_add_i32 s21, s20, 1
	s_cmp_ge_u32 s1, s26
	s_cselect_b32 s1, s21, s20
	s_xor_b32 s1, s1, s0
	s_sub_i32 s39, s1, s0
	s_mul_i32 s35, s39, s38
	s_sub_i32 s35, s33, s35
	s_lshl_b32 s34, s35, 7
	s_and_b32 s0, s34, 0xffffff00
	s_and_b32 s20, s35, 1
	v_or_b32_e32 v92, s0, v40
	s_lshl_b32 s0, s20, 5
	s_cmp_lt_i32 s27, 1
	v_or3_b32 v93, v92, s0, v41
	s_cbranch_scc1 .Lconv_41
	s_cmp_gt_i32 s27, 1
	s_cbranch_scc0 .Lconv_42
	s_cmp_eq_u32 s27, 2
	s_mov_b64 s[0:1], -1
	s_cbranch_scc0 .Lconv_40
	s_ashr_i32 s0, s34, 1
	s_mulk_i32 s20, 0xb00
	s_and_b32 s0, s0, 0xffffff80
	s_add_i32 s0, s0, s20
	v_or_b32_e32 v92, s0, v39
	s_mov_b64 s[0:1], 0

.Lconv_41:
	s_mov_b64 s[0:1], 0
	v_or_b32_e32 v94, s34, v39
	s_cbranch_execnz .Lconv_45
	s_branch .Lconv_46
.Lconv_42:
	s_mov_b64 s[0:1], 0
	s_cbranch_execz .Lconv_44
	v_mov_b32_e32 v92, v93
.Lconv_44:
	v_or_b32_e32 v94, s34, v39
	s_branch .Lconv_46
.Lconv_45:
	s_cmp_lg_u32 s27, 0
	s_cselect_b64 s[0:1], -1, 0
	v_mov_b32_e32 v92, v94
.Lconv_46:
	s_andn2_b64 vcc, exec, s[0:1]
	s_cbranch_vccnz .Lconv_48
	v_cmp_gt_i32_e32 vcc, s23, v94
	s_nop 1
	v_cndmask_b32_e32 v92, v94, v93, vcc
.Lconv_48:
	s_lshl_b32 s20, s39, 6
	v_add_u32_e32 v105, s20, v38
	v_cmp_gt_i32_e32 vcc, s4, v92
	v_ashrrev_i32_e32 v93, 31, v92
	v_lshl_add_u64 v[126:127], v[92:93], 2, s[8:9]
	v_add_u32_e32 v101, 16, v105
	v_add_u32_e32 v106, 32, v105
	v_add_u32_e32 v125, 48, v105
	v_mov_b32_e32 v76, 0
	v_mov_b32_e32 v77, 0
	v_mov_b32_e32 v78, 0
	v_mov_b32_e32 v79, 0
	v_mov_b32_e32 v80, 0
	v_mov_b32_e32 v81, 0
	v_mov_b32_e32 v82, 0
	v_mov_b32_e32 v83, 0
	v_mov_b32_e32 v84, 0
	v_mov_b32_e32 v85, 0
	v_mov_b32_e32 v86, 0
	v_mov_b32_e32 v87, 0
	v_mov_b32_e32 v88, 0
	v_mov_b32_e32 v89, 0
	v_mov_b32_e32 v90, 0
	v_mov_b32_e32 v91, 0
	v_mad_i64_i32 v[92:93], s[40:41], v105, s4, 0
	v_mad_i64_i32 v[94:95], s[40:41], v101, s4, 0
	v_mad_i64_i32 v[96:97], s[40:41], v106, s4, 0
	v_mad_i64_i32 v[98:99], s[40:41], v125, s4, 0
	v_lshl_add_u64 v[92:93], v[92:93], 2, v[126:127]
	v_lshl_add_u64 v[94:95], v[94:95], 2, v[126:127]
	v_lshl_add_u64 v[96:97], v[96:97], 2, v[126:127]
	v_lshl_add_u64 v[98:99], v[98:99], 2, v[126:127]
	s_mov_b64 s[36:37], exec
	v_cmp_gt_i32_e64 s[0:1], s5, v105
	s_nop 0
	s_and_b64 s[0:1], s[0:1], vcc
	s_and_b64 exec, s[36:37], s[0:1]
	global_load_dwordx4 v[76:79], v[92:93], off
	s_mov_b64 exec, s[36:37]
	v_cmp_gt_i32_e64 s[0:1], s5, v101
	s_nop 0
	s_and_b64 s[0:1], s[0:1], vcc
	s_and_b64 exec, s[36:37], s[0:1]
	global_load_dwordx4 v[80:83], v[94:95], off
	s_mov_b64 exec, s[36:37]
	v_cmp_gt_i32_e64 s[0:1], s5, v106
	s_nop 0
	s_and_b64 s[0:1], s[0:1], vcc
	s_and_b64 exec, s[36:37], s[0:1]
	global_load_dwordx4 v[84:87], v[96:97], off
	s_mov_b64 exec, s[36:37]
	v_cmp_gt_i32_e64 s[0:1], s5, v125
	s_nop 0
	s_and_b64 s[0:1], s[0:1], vcc
	s_and_b64 exec, s[36:37], s[0:1]
	global_load_dwordx4 v[88:91], v[98:99], off
	s_mov_b64 exec, s[36:37]
	s_mov_b64 s[0:1], 0
	v_mov_b32_e32 v105, v14
.Lconv_nopf:
	s_waitcnt lgkmcnt(7)
	v_cvt_pk_bf16_f32 v2, v2, v3
	s_waitcnt lgkmcnt(6)
	v_cvt_pk_bf16_f32 v3, v4, v5
	s_waitcnt lgkmcnt(5)
	v_cvt_pk_bf16_f32 v4, v6, v7
	s_waitcnt lgkmcnt(4)
	v_cvt_pk_bf16_f32 v5, v8, v9
	global_store_dwordx4 v[20:21], v[2:5], off
	s_waitcnt lgkmcnt(2)
	v_cvt_pk_bf16_f32 v2, v10, v11
	s_waitcnt lgkmcnt(1)
	v_cvt_pk_bf16_f32 v3, v12, v13
	v_cvt_pk_bf16_f32 v4, v16, v17
	s_waitcnt lgkmcnt(0)
	v_cvt_pk_bf16_f32 v5, v18, v19
	global_store_dwordx4 v[20:21], v[2:5], off offset:16
	s_cmp_ge_i32 s33, s7
	s_barrier
	s_cbranch_scc1 .LBB0_32
	s_branch .LBB0_35
.LBB0_36:
	s_abs_i32 s1, s33
	s_mul_hi_u32 s20, s1, s31
	s_mul_i32 s21, s20, s26
	s_ashr_i32 s0, s33, 31
	s_sub_i32 s1, s1, s21
	s_xor_b32 s0, s0, s28
	s_add_i32 s21, s20, 1
	s_sub_i32 s34, s1, s26
	s_cmp_ge_u32 s1, s26
	s_cselect_b32 s20, s21, s20
	s_cselect_b32 s1, s34, s1
	s_add_i32 s21, s20, 1
	s_cmp_ge_u32 s1, s26
	s_cselect_b32 s1, s21, s20
	s_xor_b32 s1, s1, s0
	s_sub_i32 s39, s1, s0
	s_mul_i32 s35, s39, s38
	s_sub_i32 s35, s33, s35
	s_lshl_b32 s34, s35, 7
	s_and_b32 s0, s34, 0xffffff00
	s_and_b32 s20, s35, 1
	v_or_b32_e32 v92, s0, v40
	s_lshl_b32 s0, s20, 5
	s_waitcnt lgkmcnt(0)
	s_cmp_lt_i32 s27, 1
	v_or3_b32 v93, v92, s0, v41
	s_cbranch_scc1 .LBB0_41
	s_cmp_gt_i32 s27, 1
	s_cbranch_scc0 .LBB0_42
	s_cmp_eq_u32 s27, 2
	s_mov_b64 s[0:1], -1
	s_cbranch_scc0 .LBB0_40
	s_ashr_i32 s0, s34, 1
	s_mulk_i32 s20, 0xb00
	s_and_b32 s0, s0, 0xffffff80
	s_add_i32 s0, s0, s20
	v_or_b32_e32 v92, s0, v39
	s_mov_b64 s[0:1], 0

.LBB0_48:
	s_lshl_b32 s20, s39, 6
	v_add_u32_e32 v105, s20, v38
	v_cmp_gt_i32_e32 vcc, s4, v92
	v_ashrrev_i32_e32 v93, 31, v92
	v_lshl_add_u64 v[126:127], v[92:93], 2, s[8:9]
	v_add_u32_e32 v101, 16, v105
	v_add_u32_e32 v106, 32, v105
	v_add_u32_e32 v125, 48, v105
	v_mov_b32_e32 v76, 0
	v_mov_b32_e32 v77, 0
	v_mov_b32_e32 v78, 0
	v_mov_b32_e32 v79, 0
	v_mov_b32_e32 v80, 0
	v_mov_b32_e32 v81, 0
	v_mov_b32_e32 v82, 0
	v_mov_b32_e32 v83, 0
	v_mov_b32_e32 v84, 0
	v_mov_b32_e32 v85, 0
	v_mov_b32_e32 v86, 0
	v_mov_b32_e32 v87, 0
	v_mov_b32_e32 v88, 0
	v_mov_b32_e32 v89, 0
	v_mov_b32_e32 v90, 0
	v_mov_b32_e32 v91, 0
	v_mad_i64_i32 v[92:93], s[40:41], v105, s4, 0
	v_mad_i64_i32 v[94:95], s[40:41], v101, s4, 0
	v_mad_i64_i32 v[96:97], s[40:41], v106, s4, 0
	v_mad_i64_i32 v[98:99], s[40:41], v125, s4, 0
	v_lshl_add_u64 v[92:93], v[92:93], 2, v[126:127]
	v_lshl_add_u64 v[94:95], v[94:95], 2, v[126:127]
	v_lshl_add_u64 v[96:97], v[96:97], 2, v[126:127]
	v_lshl_add_u64 v[98:99], v[98:99], 2, v[126:127]
	s_mov_b64 s[36:37], exec
	v_cmp_gt_i32_e64 s[0:1], s5, v105
	s_nop 0
	s_and_b64 s[0:1], s[0:1], vcc
	s_and_b64 exec, s[36:37], s[0:1]
	global_load_dwordx4 v[76:79], v[92:93], off
	s_mov_b64 exec, s[36:37]
	v_cmp_gt_i32_e64 s[0:1], s5, v101
	s_nop 0
	s_and_b64 s[0:1], s[0:1], vcc
	s_and_b64 exec, s[36:37], s[0:1]
	global_load_dwordx4 v[80:83], v[94:95], off
	s_mov_b64 exec, s[36:37]
	v_cmp_gt_i32_e64 s[0:1], s5, v106
	s_nop 0
	s_and_b64 s[0:1], s[0:1], vcc
	s_and_b64 exec, s[36:37], s[0:1]
	global_load_dwordx4 v[84:87], v[96:97], off
	s_mov_b64 exec, s[36:37]
	v_cmp_gt_i32_e64 s[0:1], s5, v125
	s_nop 0
	s_and_b64 s[0:1], s[0:1], vcc
	s_and_b64 exec, s[36:37], s[0:1]
	global_load_dwordx4 v[88:91], v[98:99], off
	s_mov_b64 exec, s[36:37]
	s_mov_b64 s[0:1], 0
	v_mov_b32_e32 v105, v14
	s_waitcnt vmcnt(0)
	s_branch .Lconv_b1
